# adaLN tasks remapped so the three row groups of a column group share an XCD (w_ada L2 reuse)
# speedup vs baseline: 1.0082x; 1.0082x over previous
.LBB0_75:
	s_andn2_b64 vcc, exec, s[4:5]
	s_cbranch_vccnz .LBB0_105
	s_lshr_b32 s24, s96, 3
	s_mul_i32 s25, s24, 11
	s_lshr_b32 s25, s25, 5
	s_mul_i32 s4, s25, 3
	s_sub_i32 s24, s24, s4
	s_and_b32 s4, s96, 7
	s_lshl_b32 s25, s25, 3
	s_add_i32 s25, s25, s4
	v_lshlrev_b32_e32 v2, 2, v1
	v_and_b32_e32 v2, 0x3fc, v2
	v_mov_b32_e32 v19, 0
	s_mul_i32 s24, s24, 48
	s_mov_b32 s26, 0
	v_lshl_add_u32 v22, v2, 1, 0
	v_lshlrev_b32_e32 v20, 2, v2
	v_mov_b32_e32 v21, v19
	s_movk_i32 s27, 0x810
